# diff_rows row loop rewritten by hand: all 16 rows of a wave loaded in one batch, lane sums batched over rows
# baseline (speedup 1.0000x reference)
.LBB0_398:
	v_and_b32_e32 v10, 15, v246
	v_lshrrev_b32_e32 v11, 4, v246
	v_lshlrev_b32_e32 v10, 4, v10
	s_lshl_b32 s4, s46, 11
	v_lshl_add_u32 v12, v11, 9, v10
	v_lshl_add_u32 v13, v11, 8, v10
	s_add_u32 s24, s50, s4
	s_addc_u32 s25, s51, 0
	s_add_u32 s14, s54, s4
	s_addc_u32 s15, s55, 0
	global_load_dwordx4 v[100:103], v12, s[24:25]
	global_load_dwordx4 v[104:107], v12, s[24:25] offset:256
	s_add_u32 s24, s24, 0x400000
	s_addc_u32 s25, s25, 0
	global_load_dwordx4 v[108:111], v12, s[24:25]
	global_load_dwordx4 v[112:115], v12, s[24:25] offset:256
	s_add_u32 s24, s24, 0x400000
	s_addc_u32 s25, s25, 0
	global_load_dwordx4 v[116:119], v12, s[24:25]
	global_load_dwordx4 v[120:123], v12, s[24:25] offset:256
	s_add_u32 s24, s24, 0x400000
	s_addc_u32 s25, s25, 0
	global_load_dwordx4 v[124:127], v12, s[24:25]
	global_load_dwordx4 v[128:131], v12, s[24:25] offset:256
	s_add_u32 s24, s24, 0x400000
	s_addc_u32 s25, s25, 0
	global_load_dwordx4 v[132:135], v12, s[24:25]
	global_load_dwordx4 v[136:139], v12, s[24:25] offset:256
	s_add_u32 s24, s24, 0x400000
	s_addc_u32 s25, s25, 0
	global_load_dwordx4 v[140:143], v12, s[24:25]
	global_load_dwordx4 v[144:147], v12, s[24:25] offset:256
	s_add_u32 s24, s24, 0x400000
	s_addc_u32 s25, s25, 0
	global_load_dwordx4 v[148:151], v12, s[24:25]
	global_load_dwordx4 v[152:155], v12, s[24:25] offset:256
	s_add_u32 s24, s24, 0x400000
	s_addc_u32 s25, s25, 0
	global_load_dwordx4 v[156:159], v12, s[24:25]
	global_load_dwordx4 v[160:163], v12, s[24:25] offset:256
	s_add_u32 s24, s24, 0x400000
	s_addc_u32 s25, s25, 0
	global_load_dwordx4 v[164:167], v12, s[24:25]
	global_load_dwordx4 v[168:171], v12, s[24:25] offset:256
	s_add_u32 s24, s24, 0x400000
	s_addc_u32 s25, s25, 0
	global_load_dwordx4 v[172:175], v12, s[24:25]
	global_load_dwordx4 v[176:179], v12, s[24:25] offset:256
	s_add_u32 s24, s24, 0x400000
	s_addc_u32 s25, s25, 0
	global_load_dwordx4 v[180:183], v12, s[24:25]
	global_load_dwordx4 v[184:187], v12, s[24:25] offset:256
	s_add_u32 s24, s24, 0x400000
	s_addc_u32 s25, s25, 0
	global_load_dwordx4 v[188:191], v12, s[24:25]
	global_load_dwordx4 v[192:195], v12, s[24:25] offset:256
	s_add_u32 s24, s24, 0x400000
	s_addc_u32 s25, s25, 0
	global_load_dwordx4 v[196:199], v12, s[24:25]
	global_load_dwordx4 v[200:203], v12, s[24:25] offset:256
	s_add_u32 s24, s24, 0x400000
	s_addc_u32 s25, s25, 0
	global_load_dwordx4 v[204:207], v12, s[24:25]
	global_load_dwordx4 v[208:211], v12, s[24:25] offset:256
	s_add_u32 s24, s24, 0x400000
	s_addc_u32 s25, s25, 0
	global_load_dwordx4 v[212:215], v12, s[24:25]
	global_load_dwordx4 v[216:219], v12, s[24:25] offset:256
	s_add_u32 s24, s24, 0x400000
	s_addc_u32 s25, s25, 0
	global_load_dwordx4 v[220:223], v12, s[24:25]
	global_load_dwordx4 v[224:227], v12, s[24:25] offset:256
	s_waitcnt vmcnt(30) lgkmcnt(0)
	v_lshlrev_b32_e32 v54, 16, v104
	v_and_b32_e32 v55, 0xffff0000, v104
	v_lshlrev_b32_e32 v56, 16, v105
	v_and_b32_e32 v57, 0xffff0000, v105
	v_lshlrev_b32_e32 v58, 16, v106
	v_and_b32_e32 v59, 0xffff0000, v106
	v_lshlrev_b32_e32 v60, 16, v107
	v_and_b32_e32 v61, 0xffff0000, v107
	v_lshlrev_b32_e32 v106, 16, v103
	v_and_b32_e32 v107, 0xffff0000, v103
	v_lshlrev_b32_e32 v104, 16, v102
	v_and_b32_e32 v105, 0xffff0000, v102
	v_and_b32_e32 v103, 0xffff0000, v101
	v_lshlrev_b32_e32 v102, 16, v101
	v_and_b32_e32 v101, 0xffff0000, v100
	v_lshlrev_b32_e32 v100, 16, v100
	v_pk_fma_f32 v[100:101], v[42:43], v[54:55], v[100:101] neg_lo:[1,0,0] neg_hi:[1,0,0]
	v_pk_fma_f32 v[102:103], v[42:43], v[56:57], v[102:103] neg_lo:[1,0,0] neg_hi:[1,0,0]
	v_pk_fma_f32 v[104:105], v[42:43], v[58:59], v[104:105] neg_lo:[1,0,0] neg_hi:[1,0,0]
	v_pk_fma_f32 v[106:107], v[42:43], v[60:61], v[106:107] neg_lo:[1,0,0] neg_hi:[1,0,0]
	v_mul_f32_e32 v54, v101, v101
	v_mul_f32_e32 v55, v103, v103
	v_mul_f32_e32 v56, v105, v105
	v_mul_f32_e32 v57, v107, v107
	v_fma_f32 v54, v100, v100, v54
	v_fma_f32 v55, v102, v102, v55
	v_fma_f32 v56, v104, v104, v56
	v_fma_f32 v57, v106, v106, v57
	v_add_f32_e32 v54, v54, v55
	v_add_f32_e32 v56, v56, v57
	v_add_f32_e32 v62, v54, v56
	s_waitcnt vmcnt(28)
	v_lshlrev_b32_e32 v54, 16, v112
	v_and_b32_e32 v55, 0xffff0000, v112
	v_lshlrev_b32_e32 v56, 16, v113
	v_and_b32_e32 v57, 0xffff0000, v113
	v_lshlrev_b32_e32 v58, 16, v114
	v_and_b32_e32 v59, 0xffff0000, v114
	v_lshlrev_b32_e32 v60, 16, v115
	v_and_b32_e32 v61, 0xffff0000, v115
	v_lshlrev_b32_e32 v114, 16, v111
	v_and_b32_e32 v115, 0xffff0000, v111
	v_lshlrev_b32_e32 v112, 16, v110
	v_and_b32_e32 v113, 0xffff0000, v110
	v_and_b32_e32 v111, 0xffff0000, v109
	v_lshlrev_b32_e32 v110, 16, v109
	v_and_b32_e32 v109, 0xffff0000, v108
	v_lshlrev_b32_e32 v108, 16, v108
	v_pk_fma_f32 v[108:109], v[42:43], v[54:55], v[108:109] neg_lo:[1,0,0] neg_hi:[1,0,0]
	v_pk_fma_f32 v[110:111], v[42:43], v[56:57], v[110:111] neg_lo:[1,0,0] neg_hi:[1,0,0]
	v_pk_fma_f32 v[112:113], v[42:43], v[58:59], v[112:113] neg_lo:[1,0,0] neg_hi:[1,0,0]
	v_pk_fma_f32 v[114:115], v[42:43], v[60:61], v[114:115] neg_lo:[1,0,0] neg_hi:[1,0,0]
	v_mul_f32_e32 v54, v109, v109
	v_mul_f32_e32 v55, v111, v111
	v_mul_f32_e32 v56, v113, v113
	v_mul_f32_e32 v57, v115, v115
	v_fma_f32 v54, v108, v108, v54
	v_fma_f32 v55, v110, v110, v55
	v_fma_f32 v56, v112, v112, v56
	v_fma_f32 v57, v114, v114, v57
	v_add_f32_e32 v54, v54, v55
	v_add_f32_e32 v56, v56, v57
	v_add_f32_e32 v63, v54, v56
	s_waitcnt vmcnt(26)
	v_lshlrev_b32_e32 v54, 16, v120
	v_and_b32_e32 v55, 0xffff0000, v120
	v_lshlrev_b32_e32 v56, 16, v121
	v_and_b32_e32 v57, 0xffff0000, v121
	v_lshlrev_b32_e32 v58, 16, v122
	v_and_b32_e32 v59, 0xffff0000, v122
	v_lshlrev_b32_e32 v60, 16, v123
	v_and_b32_e32 v61, 0xffff0000, v123
	v_lshlrev_b32_e32 v122, 16, v119
	v_and_b32_e32 v123, 0xffff0000, v119
	v_lshlrev_b32_e32 v120, 16, v118
	v_and_b32_e32 v121, 0xffff0000, v118
	v_and_b32_e32 v119, 0xffff0000, v117
	v_lshlrev_b32_e32 v118, 16, v117
	v_and_b32_e32 v117, 0xffff0000, v116
	v_lshlrev_b32_e32 v116, 16, v116
	v_pk_fma_f32 v[116:117], v[42:43], v[54:55], v[116:117] neg_lo:[1,0,0] neg_hi:[1,0,0]
	v_pk_fma_f32 v[118:119], v[42:43], v[56:57], v[118:119] neg_lo:[1,0,0] neg_hi:[1,0,0]
	v_pk_fma_f32 v[120:121], v[42:43], v[58:59], v[120:121] neg_lo:[1,0,0] neg_hi:[1,0,0]
	v_pk_fma_f32 v[122:123], v[42:43], v[60:61], v[122:123] neg_lo:[1,0,0] neg_hi:[1,0,0]
	v_mul_f32_e32 v54, v117, v117
	v_mul_f32_e32 v55, v119, v119
	v_mul_f32_e32 v56, v121, v121
	v_mul_f32_e32 v57, v123, v123
	v_fma_f32 v54, v116, v116, v54
	v_fma_f32 v55, v118, v118, v55
	v_fma_f32 v56, v120, v120, v56
	v_fma_f32 v57, v122, v122, v57
	v_add_f32_e32 v54, v54, v55
	v_add_f32_e32 v56, v56, v57
	v_add_f32_e32 v64, v54, v56
	s_waitcnt vmcnt(24)
	v_lshlrev_b32_e32 v54, 16, v128
	v_and_b32_e32 v55, 0xffff0000, v128
	v_lshlrev_b32_e32 v56, 16, v129
	v_and_b32_e32 v57, 0xffff0000, v129
	v_lshlrev_b32_e32 v58, 16, v130
	v_and_b32_e32 v59, 0xffff0000, v130
	v_lshlrev_b32_e32 v60, 16, v131
	v_and_b32_e32 v61, 0xffff0000, v131
	v_lshlrev_b32_e32 v130, 16, v127
	v_and_b32_e32 v131, 0xffff0000, v127
	v_lshlrev_b32_e32 v128, 16, v126
	v_and_b32_e32 v129, 0xffff0000, v126
	v_and_b32_e32 v127, 0xffff0000, v125
	v_lshlrev_b32_e32 v126, 16, v125
	v_and_b32_e32 v125, 0xffff0000, v124
	v_lshlrev_b32_e32 v124, 16, v124
	v_pk_fma_f32 v[124:125], v[42:43], v[54:55], v[124:125] neg_lo:[1,0,0] neg_hi:[1,0,0]
	v_pk_fma_f32 v[126:127], v[42:43], v[56:57], v[126:127] neg_lo:[1,0,0] neg_hi:[1,0,0]
	v_pk_fma_f32 v[128:129], v[42:43], v[58:59], v[128:129] neg_lo:[1,0,0] neg_hi:[1,0,0]
	v_pk_fma_f32 v[130:131], v[42:43], v[60:61], v[130:131] neg_lo:[1,0,0] neg_hi:[1,0,0]
	v_mul_f32_e32 v54, v125, v125
	v_mul_f32_e32 v55, v127, v127
	v_mul_f32_e32 v56, v129, v129
	v_mul_f32_e32 v57, v131, v131
	v_fma_f32 v54, v124, v124, v54
	v_fma_f32 v55, v126, v126, v55
	v_fma_f32 v56, v128, v128, v56
	v_fma_f32 v57, v130, v130, v57
	v_add_f32_e32 v54, v54, v55
	v_add_f32_e32 v56, v56, v57
	v_add_f32_e32 v65, v54, v56
	s_waitcnt vmcnt(22)
	v_lshlrev_b32_e32 v54, 16, v136
	v_and_b32_e32 v55, 0xffff0000, v136
	v_lshlrev_b32_e32 v56, 16, v137
	v_and_b32_e32 v57, 0xffff0000, v137
	v_lshlrev_b32_e32 v58, 16, v138
	v_and_b32_e32 v59, 0xffff0000, v138
	v_lshlrev_b32_e32 v60, 16, v139
	v_and_b32_e32 v61, 0xffff0000, v139
	v_lshlrev_b32_e32 v138, 16, v135
	v_and_b32_e32 v139, 0xffff0000, v135
	v_lshlrev_b32_e32 v136, 16, v134
	v_and_b32_e32 v137, 0xffff0000, v134
	v_and_b32_e32 v135, 0xffff0000, v133
	v_lshlrev_b32_e32 v134, 16, v133
	v_and_b32_e32 v133, 0xffff0000, v132
	v_lshlrev_b32_e32 v132, 16, v132
	v_pk_fma_f32 v[132:133], v[42:43], v[54:55], v[132:133] neg_lo:[1,0,0] neg_hi:[1,0,0]
	v_pk_fma_f32 v[134:135], v[42:43], v[56:57], v[134:135] neg_lo:[1,0,0] neg_hi:[1,0,0]
	v_pk_fma_f32 v[136:137], v[42:43], v[58:59], v[136:137] neg_lo:[1,0,0] neg_hi:[1,0,0]
	v_pk_fma_f32 v[138:139], v[42:43], v[60:61], v[138:139] neg_lo:[1,0,0] neg_hi:[1,0,0]
	v_mul_f32_e32 v54, v133, v133
	v_mul_f32_e32 v55, v135, v135
	v_mul_f32_e32 v56, v137, v137
	v_mul_f32_e32 v57, v139, v139
	v_fma_f32 v54, v132, v132, v54
	v_fma_f32 v55, v134, v134, v55
	v_fma_f32 v56, v136, v136, v56
	v_fma_f32 v57, v138, v138, v57
	v_add_f32_e32 v54, v54, v55
	v_add_f32_e32 v56, v56, v57
	v_add_f32_e32 v66, v54, v56
	s_waitcnt vmcnt(20)
	v_lshlrev_b32_e32 v54, 16, v144
	v_and_b32_e32 v55, 0xffff0000, v144
	v_lshlrev_b32_e32 v56, 16, v145
	v_and_b32_e32 v57, 0xffff0000, v145
	v_lshlrev_b32_e32 v58, 16, v146
	v_and_b32_e32 v59, 0xffff0000, v146
	v_lshlrev_b32_e32 v60, 16, v147
	v_and_b32_e32 v61, 0xffff0000, v147
	v_lshlrev_b32_e32 v146, 16, v143
	v_and_b32_e32 v147, 0xffff0000, v143
	v_lshlrev_b32_e32 v144, 16, v142
	v_and_b32_e32 v145, 0xffff0000, v142
	v_and_b32_e32 v143, 0xffff0000, v141
	v_lshlrev_b32_e32 v142, 16, v141
	v_and_b32_e32 v141, 0xffff0000, v140
	v_lshlrev_b32_e32 v140, 16, v140
	v_pk_fma_f32 v[140:141], v[42:43], v[54:55], v[140:141] neg_lo:[1,0,0] neg_hi:[1,0,0]
	v_pk_fma_f32 v[142:143], v[42:43], v[56:57], v[142:143] neg_lo:[1,0,0] neg_hi:[1,0,0]
	v_pk_fma_f32 v[144:145], v[42:43], v[58:59], v[144:145] neg_lo:[1,0,0] neg_hi:[1,0,0]
	v_pk_fma_f32 v[146:147], v[42:43], v[60:61], v[146:147] neg_lo:[1,0,0] neg_hi:[1,0,0]
	v_mul_f32_e32 v54, v141, v141
	v_mul_f32_e32 v55, v143, v143
	v_mul_f32_e32 v56, v145, v145
	v_mul_f32_e32 v57, v147, v147
	v_fma_f32 v54, v140, v140, v54
	v_fma_f32 v55, v142, v142, v55
	v_fma_f32 v56, v144, v144, v56
	v_fma_f32 v57, v146, v146, v57
	v_add_f32_e32 v54, v54, v55
	v_add_f32_e32 v56, v56, v57
	v_add_f32_e32 v67, v54, v56
	s_waitcnt vmcnt(18)
	v_lshlrev_b32_e32 v54, 16, v152
	v_and_b32_e32 v55, 0xffff0000, v152
	v_lshlrev_b32_e32 v56, 16, v153
	v_and_b32_e32 v57, 0xffff0000, v153
	v_lshlrev_b32_e32 v58, 16, v154
	v_and_b32_e32 v59, 0xffff0000, v154
	v_lshlrev_b32_e32 v60, 16, v155
	v_and_b32_e32 v61, 0xffff0000, v155
	v_lshlrev_b32_e32 v154, 16, v151
	v_and_b32_e32 v155, 0xffff0000, v151
	v_lshlrev_b32_e32 v152, 16, v150
	v_and_b32_e32 v153, 0xffff0000, v150
	v_and_b32_e32 v151, 0xffff0000, v149
	v_lshlrev_b32_e32 v150, 16, v149
	v_and_b32_e32 v149, 0xffff0000, v148
	v_lshlrev_b32_e32 v148, 16, v148
	v_pk_fma_f32 v[148:149], v[42:43], v[54:55], v[148:149] neg_lo:[1,0,0] neg_hi:[1,0,0]
	v_pk_fma_f32 v[150:151], v[42:43], v[56:57], v[150:151] neg_lo:[1,0,0] neg_hi:[1,0,0]
	v_pk_fma_f32 v[152:153], v[42:43], v[58:59], v[152:153] neg_lo:[1,0,0] neg_hi:[1,0,0]
	v_pk_fma_f32 v[154:155], v[42:43], v[60:61], v[154:155] neg_lo:[1,0,0] neg_hi:[1,0,0]
	v_mul_f32_e32 v54, v149, v149
	v_mul_f32_e32 v55, v151, v151
	v_mul_f32_e32 v56, v153, v153
	v_mul_f32_e32 v57, v155, v155
	v_fma_f32 v54, v148, v148, v54
	v_fma_f32 v55, v150, v150, v55
	v_fma_f32 v56, v152, v152, v56
	v_fma_f32 v57, v154, v154, v57
	v_add_f32_e32 v54, v54, v55
	v_add_f32_e32 v56, v56, v57
	v_add_f32_e32 v68, v54, v56
	s_waitcnt vmcnt(16)
	v_lshlrev_b32_e32 v54, 16, v160
	v_and_b32_e32 v55, 0xffff0000, v160
	v_lshlrev_b32_e32 v56, 16, v161
	v_and_b32_e32 v57, 0xffff0000, v161
	v_lshlrev_b32_e32 v58, 16, v162
	v_and_b32_e32 v59, 0xffff0000, v162
	v_lshlrev_b32_e32 v60, 16, v163
	v_and_b32_e32 v61, 0xffff0000, v163
	v_lshlrev_b32_e32 v162, 16, v159
	v_and_b32_e32 v163, 0xffff0000, v159
	v_lshlrev_b32_e32 v160, 16, v158
	v_and_b32_e32 v161, 0xffff0000, v158
	v_and_b32_e32 v159, 0xffff0000, v157
	v_lshlrev_b32_e32 v158, 16, v157
	v_and_b32_e32 v157, 0xffff0000, v156
	v_lshlrev_b32_e32 v156, 16, v156
	v_pk_fma_f32 v[156:157], v[42:43], v[54:55], v[156:157] neg_lo:[1,0,0] neg_hi:[1,0,0]
	v_pk_fma_f32 v[158:159], v[42:43], v[56:57], v[158:159] neg_lo:[1,0,0] neg_hi:[1,0,0]
	v_pk_fma_f32 v[160:161], v[42:43], v[58:59], v[160:161] neg_lo:[1,0,0] neg_hi:[1,0,0]
	v_pk_fma_f32 v[162:163], v[42:43], v[60:61], v[162:163] neg_lo:[1,0,0] neg_hi:[1,0,0]
	v_mul_f32_e32 v54, v157, v157
	v_mul_f32_e32 v55, v159, v159
	v_mul_f32_e32 v56, v161, v161
	v_mul_f32_e32 v57, v163, v163
	v_fma_f32 v54, v156, v156, v54
	v_fma_f32 v55, v158, v158, v55
	v_fma_f32 v56, v160, v160, v56
	v_fma_f32 v57, v162, v162, v57
	v_add_f32_e32 v54, v54, v55
	v_add_f32_e32 v56, v56, v57
	v_add_f32_e32 v69, v54, v56
	s_waitcnt vmcnt(14)
	v_lshlrev_b32_e32 v54, 16, v168
	v_and_b32_e32 v55, 0xffff0000, v168
	v_lshlrev_b32_e32 v56, 16, v169
	v_and_b32_e32 v57, 0xffff0000, v169
	v_lshlrev_b32_e32 v58, 16, v170
	v_and_b32_e32 v59, 0xffff0000, v170
	v_lshlrev_b32_e32 v60, 16, v171
	v_and_b32_e32 v61, 0xffff0000, v171
	v_lshlrev_b32_e32 v170, 16, v167
	v_and_b32_e32 v171, 0xffff0000, v167
	v_lshlrev_b32_e32 v168, 16, v166
	v_and_b32_e32 v169, 0xffff0000, v166
	v_and_b32_e32 v167, 0xffff0000, v165
	v_lshlrev_b32_e32 v166, 16, v165
	v_and_b32_e32 v165, 0xffff0000, v164
	v_lshlrev_b32_e32 v164, 16, v164
	v_pk_fma_f32 v[164:165], v[42:43], v[54:55], v[164:165] neg_lo:[1,0,0] neg_hi:[1,0,0]
	v_pk_fma_f32 v[166:167], v[42:43], v[56:57], v[166:167] neg_lo:[1,0,0] neg_hi:[1,0,0]
	v_pk_fma_f32 v[168:169], v[42:43], v[58:59], v[168:169] neg_lo:[1,0,0] neg_hi:[1,0,0]
	v_pk_fma_f32 v[170:171], v[42:43], v[60:61], v[170:171] neg_lo:[1,0,0] neg_hi:[1,0,0]
	v_mul_f32_e32 v54, v165, v165
	v_mul_f32_e32 v55, v167, v167
	v_mul_f32_e32 v56, v169, v169
	v_mul_f32_e32 v57, v171, v171
	v_fma_f32 v54, v164, v164, v54
	v_fma_f32 v55, v166, v166, v55
	v_fma_f32 v56, v168, v168, v56
	v_fma_f32 v57, v170, v170, v57
	v_add_f32_e32 v54, v54, v55
	v_add_f32_e32 v56, v56, v57
	v_add_f32_e32 v70, v54, v56
	s_waitcnt vmcnt(12)
	v_lshlrev_b32_e32 v54, 16, v176
	v_and_b32_e32 v55, 0xffff0000, v176
	v_lshlrev_b32_e32 v56, 16, v177
	v_and_b32_e32 v57, 0xffff0000, v177
	v_lshlrev_b32_e32 v58, 16, v178
	v_and_b32_e32 v59, 0xffff0000, v178
	v_lshlrev_b32_e32 v60, 16, v179
	v_and_b32_e32 v61, 0xffff0000, v179
	v_lshlrev_b32_e32 v178, 16, v175
	v_and_b32_e32 v179, 0xffff0000, v175
	v_lshlrev_b32_e32 v176, 16, v174
	v_and_b32_e32 v177, 0xffff0000, v174
	v_and_b32_e32 v175, 0xffff0000, v173
	v_lshlrev_b32_e32 v174, 16, v173
	v_and_b32_e32 v173, 0xffff0000, v172
	v_lshlrev_b32_e32 v172, 16, v172
	v_pk_fma_f32 v[172:173], v[42:43], v[54:55], v[172:173] neg_lo:[1,0,0] neg_hi:[1,0,0]
	v_pk_fma_f32 v[174:175], v[42:43], v[56:57], v[174:175] neg_lo:[1,0,0] neg_hi:[1,0,0]
	v_pk_fma_f32 v[176:177], v[42:43], v[58:59], v[176:177] neg_lo:[1,0,0] neg_hi:[1,0,0]
	v_pk_fma_f32 v[178:179], v[42:43], v[60:61], v[178:179] neg_lo:[1,0,0] neg_hi:[1,0,0]
	v_mul_f32_e32 v54, v173, v173
	v_mul_f32_e32 v55, v175, v175
	v_mul_f32_e32 v56, v177, v177
	v_mul_f32_e32 v57, v179, v179
	v_fma_f32 v54, v172, v172, v54
	v_fma_f32 v55, v174, v174, v55
	v_fma_f32 v56, v176, v176, v56
	v_fma_f32 v57, v178, v178, v57
	v_add_f32_e32 v54, v54, v55
	v_add_f32_e32 v56, v56, v57
	v_add_f32_e32 v71, v54, v56
	s_waitcnt vmcnt(10)
	v_lshlrev_b32_e32 v54, 16, v184
	v_and_b32_e32 v55, 0xffff0000, v184
	v_lshlrev_b32_e32 v56, 16, v185
	v_and_b32_e32 v57, 0xffff0000, v185
	v_lshlrev_b32_e32 v58, 16, v186
	v_and_b32_e32 v59, 0xffff0000, v186
	v_lshlrev_b32_e32 v60, 16, v187
	v_and_b32_e32 v61, 0xffff0000, v187
	v_lshlrev_b32_e32 v186, 16, v183
	v_and_b32_e32 v187, 0xffff0000, v183
	v_lshlrev_b32_e32 v184, 16, v182
	v_and_b32_e32 v185, 0xffff0000, v182
	v_and_b32_e32 v183, 0xffff0000, v181
	v_lshlrev_b32_e32 v182, 16, v181
	v_and_b32_e32 v181, 0xffff0000, v180
	v_lshlrev_b32_e32 v180, 16, v180
	v_pk_fma_f32 v[180:181], v[42:43], v[54:55], v[180:181] neg_lo:[1,0,0] neg_hi:[1,0,0]
	v_pk_fma_f32 v[182:183], v[42:43], v[56:57], v[182:183] neg_lo:[1,0,0] neg_hi:[1,0,0]
	v_pk_fma_f32 v[184:185], v[42:43], v[58:59], v[184:185] neg_lo:[1,0,0] neg_hi:[1,0,0]
	v_pk_fma_f32 v[186:187], v[42:43], v[60:61], v[186:187] neg_lo:[1,0,0] neg_hi:[1,0,0]
	v_mul_f32_e32 v54, v181, v181
	v_mul_f32_e32 v55, v183, v183
	v_mul_f32_e32 v56, v185, v185
	v_mul_f32_e32 v57, v187, v187
	v_fma_f32 v54, v180, v180, v54
	v_fma_f32 v55, v182, v182, v55
	v_fma_f32 v56, v184, v184, v56
	v_fma_f32 v57, v186, v186, v57
	v_add_f32_e32 v54, v54, v55
	v_add_f32_e32 v56, v56, v57
	v_add_f32_e32 v72, v54, v56
	s_waitcnt vmcnt(8)
	v_lshlrev_b32_e32 v54, 16, v192
	v_and_b32_e32 v55, 0xffff0000, v192
	v_lshlrev_b32_e32 v56, 16, v193
	v_and_b32_e32 v57, 0xffff0000, v193
	v_lshlrev_b32_e32 v58, 16, v194
	v_and_b32_e32 v59, 0xffff0000, v194
	v_lshlrev_b32_e32 v60, 16, v195
	v_and_b32_e32 v61, 0xffff0000, v195
	v_lshlrev_b32_e32 v194, 16, v191
	v_and_b32_e32 v195, 0xffff0000, v191
	v_lshlrev_b32_e32 v192, 16, v190
	v_and_b32_e32 v193, 0xffff0000, v190
	v_and_b32_e32 v191, 0xffff0000, v189
	v_lshlrev_b32_e32 v190, 16, v189
	v_and_b32_e32 v189, 0xffff0000, v188
	v_lshlrev_b32_e32 v188, 16, v188
	v_pk_fma_f32 v[188:189], v[42:43], v[54:55], v[188:189] neg_lo:[1,0,0] neg_hi:[1,0,0]
	v_pk_fma_f32 v[190:191], v[42:43], v[56:57], v[190:191] neg_lo:[1,0,0] neg_hi:[1,0,0]
	v_pk_fma_f32 v[192:193], v[42:43], v[58:59], v[192:193] neg_lo:[1,0,0] neg_hi:[1,0,0]
	v_pk_fma_f32 v[194:195], v[42:43], v[60:61], v[194:195] neg_lo:[1,0,0] neg_hi:[1,0,0]
	v_mul_f32_e32 v54, v189, v189
	v_mul_f32_e32 v55, v191, v191
	v_mul_f32_e32 v56, v193, v193
	v_mul_f32_e32 v57, v195, v195
	v_fma_f32 v54, v188, v188, v54
	v_fma_f32 v55, v190, v190, v55
	v_fma_f32 v56, v192, v192, v56
	v_fma_f32 v57, v194, v194, v57
	v_add_f32_e32 v54, v54, v55
	v_add_f32_e32 v56, v56, v57
	v_add_f32_e32 v73, v54, v56
	s_waitcnt vmcnt(6)
	v_lshlrev_b32_e32 v54, 16, v200
	v_and_b32_e32 v55, 0xffff0000, v200
	v_lshlrev_b32_e32 v56, 16, v201
	v_and_b32_e32 v57, 0xffff0000, v201
	v_lshlrev_b32_e32 v58, 16, v202
	v_and_b32_e32 v59, 0xffff0000, v202
	v_lshlrev_b32_e32 v60, 16, v203
	v_and_b32_e32 v61, 0xffff0000, v203
	v_lshlrev_b32_e32 v202, 16, v199
	v_and_b32_e32 v203, 0xffff0000, v199
	v_lshlrev_b32_e32 v200, 16, v198
	v_and_b32_e32 v201, 0xffff0000, v198
	v_and_b32_e32 v199, 0xffff0000, v197
	v_lshlrev_b32_e32 v198, 16, v197
	v_and_b32_e32 v197, 0xffff0000, v196
	v_lshlrev_b32_e32 v196, 16, v196
	v_pk_fma_f32 v[196:197], v[42:43], v[54:55], v[196:197] neg_lo:[1,0,0] neg_hi:[1,0,0]
	v_pk_fma_f32 v[198:199], v[42:43], v[56:57], v[198:199] neg_lo:[1,0,0] neg_hi:[1,0,0]
	v_pk_fma_f32 v[200:201], v[42:43], v[58:59], v[200:201] neg_lo:[1,0,0] neg_hi:[1,0,0]
	v_pk_fma_f32 v[202:203], v[42:43], v[60:61], v[202:203] neg_lo:[1,0,0] neg_hi:[1,0,0]
	v_mul_f32_e32 v54, v197, v197
	v_mul_f32_e32 v55, v199, v199
	v_mul_f32_e32 v56, v201, v201
	v_mul_f32_e32 v57, v203, v203
	v_fma_f32 v54, v196, v196, v54
	v_fma_f32 v55, v198, v198, v55
	v_fma_f32 v56, v200, v200, v56
	v_fma_f32 v57, v202, v202, v57
	v_add_f32_e32 v54, v54, v55
	v_add_f32_e32 v56, v56, v57
	v_add_f32_e32 v74, v54, v56
	s_waitcnt vmcnt(4)
	v_lshlrev_b32_e32 v54, 16, v208
	v_and_b32_e32 v55, 0xffff0000, v208
	v_lshlrev_b32_e32 v56, 16, v209
	v_and_b32_e32 v57, 0xffff0000, v209
	v_lshlrev_b32_e32 v58, 16, v210
	v_and_b32_e32 v59, 0xffff0000, v210
	v_lshlrev_b32_e32 v60, 16, v211
	v_and_b32_e32 v61, 0xffff0000, v211
	v_lshlrev_b32_e32 v210, 16, v207
	v_and_b32_e32 v211, 0xffff0000, v207
	v_lshlrev_b32_e32 v208, 16, v206
	v_and_b32_e32 v209, 0xffff0000, v206
	v_and_b32_e32 v207, 0xffff0000, v205
	v_lshlrev_b32_e32 v206, 16, v205
	v_and_b32_e32 v205, 0xffff0000, v204
	v_lshlrev_b32_e32 v204, 16, v204
	v_pk_fma_f32 v[204:205], v[42:43], v[54:55], v[204:205] neg_lo:[1,0,0] neg_hi:[1,0,0]
	v_pk_fma_f32 v[206:207], v[42:43], v[56:57], v[206:207] neg_lo:[1,0,0] neg_hi:[1,0,0]
	v_pk_fma_f32 v[208:209], v[42:43], v[58:59], v[208:209] neg_lo:[1,0,0] neg_hi:[1,0,0]
	v_pk_fma_f32 v[210:211], v[42:43], v[60:61], v[210:211] neg_lo:[1,0,0] neg_hi:[1,0,0]
	v_mul_f32_e32 v54, v205, v205
	v_mul_f32_e32 v55, v207, v207
	v_mul_f32_e32 v56, v209, v209
	v_mul_f32_e32 v57, v211, v211
	v_fma_f32 v54, v204, v204, v54
	v_fma_f32 v55, v206, v206, v55
	v_fma_f32 v56, v208, v208, v56
	v_fma_f32 v57, v210, v210, v57
	v_add_f32_e32 v54, v54, v55
	v_add_f32_e32 v56, v56, v57
	v_add_f32_e32 v75, v54, v56
	s_waitcnt vmcnt(2)
	v_lshlrev_b32_e32 v54, 16, v216
	v_and_b32_e32 v55, 0xffff0000, v216
	v_lshlrev_b32_e32 v56, 16, v217
	v_and_b32_e32 v57, 0xffff0000, v217
	v_lshlrev_b32_e32 v58, 16, v218
	v_and_b32_e32 v59, 0xffff0000, v218
	v_lshlrev_b32_e32 v60, 16, v219
	v_and_b32_e32 v61, 0xffff0000, v219
	v_lshlrev_b32_e32 v218, 16, v215
	v_and_b32_e32 v219, 0xffff0000, v215
	v_lshlrev_b32_e32 v216, 16, v214
	v_and_b32_e32 v217, 0xffff0000, v214
	v_and_b32_e32 v215, 0xffff0000, v213
	v_lshlrev_b32_e32 v214, 16, v213
	v_and_b32_e32 v213, 0xffff0000, v212
	v_lshlrev_b32_e32 v212, 16, v212
	v_pk_fma_f32 v[212:213], v[42:43], v[54:55], v[212:213] neg_lo:[1,0,0] neg_hi:[1,0,0]
	v_pk_fma_f32 v[214:215], v[42:43], v[56:57], v[214:215] neg_lo:[1,0,0] neg_hi:[1,0,0]
	v_pk_fma_f32 v[216:217], v[42:43], v[58:59], v[216:217] neg_lo:[1,0,0] neg_hi:[1,0,0]
	v_pk_fma_f32 v[218:219], v[42:43], v[60:61], v[218:219] neg_lo:[1,0,0] neg_hi:[1,0,0]
	v_mul_f32_e32 v54, v213, v213
	v_mul_f32_e32 v55, v215, v215
	v_mul_f32_e32 v56, v217, v217
	v_mul_f32_e32 v57, v219, v219
	v_fma_f32 v54, v212, v212, v54
	v_fma_f32 v55, v214, v214, v55
	v_fma_f32 v56, v216, v216, v56
	v_fma_f32 v57, v218, v218, v57
	v_add_f32_e32 v54, v54, v55
	v_add_f32_e32 v56, v56, v57
	v_add_f32_e32 v76, v54, v56
	s_waitcnt vmcnt(0)
	v_lshlrev_b32_e32 v54, 16, v224
	v_and_b32_e32 v55, 0xffff0000, v224
	v_lshlrev_b32_e32 v56, 16, v225
	v_and_b32_e32 v57, 0xffff0000, v225
	v_lshlrev_b32_e32 v58, 16, v226
	v_and_b32_e32 v59, 0xffff0000, v226
	v_lshlrev_b32_e32 v60, 16, v227
	v_and_b32_e32 v61, 0xffff0000, v227
	v_lshlrev_b32_e32 v226, 16, v223
	v_and_b32_e32 v227, 0xffff0000, v223
	v_lshlrev_b32_e32 v224, 16, v222
	v_and_b32_e32 v225, 0xffff0000, v222
	v_and_b32_e32 v223, 0xffff0000, v221
	v_lshlrev_b32_e32 v222, 16, v221
	v_and_b32_e32 v221, 0xffff0000, v220
	v_lshlrev_b32_e32 v220, 16, v220
	v_pk_fma_f32 v[220:221], v[42:43], v[54:55], v[220:221] neg_lo:[1,0,0] neg_hi:[1,0,0]
	v_pk_fma_f32 v[222:223], v[42:43], v[56:57], v[222:223] neg_lo:[1,0,0] neg_hi:[1,0,0]
	v_pk_fma_f32 v[224:225], v[42:43], v[58:59], v[224:225] neg_lo:[1,0,0] neg_hi:[1,0,0]
	v_pk_fma_f32 v[226:227], v[42:43], v[60:61], v[226:227] neg_lo:[1,0,0] neg_hi:[1,0,0]
	v_mul_f32_e32 v54, v221, v221
	v_mul_f32_e32 v55, v223, v223
	v_mul_f32_e32 v56, v225, v225
	v_mul_f32_e32 v57, v227, v227
	v_fma_f32 v54, v220, v220, v54
	v_fma_f32 v55, v222, v222, v55
	v_fma_f32 v56, v224, v224, v56
	v_fma_f32 v57, v226, v226, v57
	v_add_f32_e32 v54, v54, v55
	v_add_f32_e32 v56, v56, v57
	v_add_f32_e32 v77, v54, v56
	ds_bpermute_b32 v78, v8, v62
	ds_bpermute_b32 v79, v8, v63
	ds_bpermute_b32 v80, v8, v64
	ds_bpermute_b32 v81, v8, v65
	ds_bpermute_b32 v82, v8, v66
	ds_bpermute_b32 v83, v8, v67
	ds_bpermute_b32 v84, v8, v68
	ds_bpermute_b32 v85, v8, v69
	s_waitcnt lgkmcnt(0)
	v_add_f32_e32 v62, v62, v78
	v_add_f32_e32 v63, v63, v79
	v_add_f32_e32 v64, v64, v80
	v_add_f32_e32 v65, v65, v81
	v_add_f32_e32 v66, v66, v82
	v_add_f32_e32 v67, v67, v83
	v_add_f32_e32 v68, v68, v84
	v_add_f32_e32 v69, v69, v85
	ds_bpermute_b32 v86, v8, v70
	ds_bpermute_b32 v87, v8, v71
	ds_bpermute_b32 v88, v8, v72
	ds_bpermute_b32 v89, v8, v73
	ds_bpermute_b32 v90, v8, v74
	ds_bpermute_b32 v91, v8, v75
	ds_bpermute_b32 v92, v8, v76
	ds_bpermute_b32 v93, v8, v77
	s_waitcnt lgkmcnt(0)
	v_add_f32_e32 v70, v70, v86
	v_add_f32_e32 v71, v71, v87
	v_add_f32_e32 v72, v72, v88
	v_add_f32_e32 v73, v73, v89
	v_add_f32_e32 v74, v74, v90
	v_add_f32_e32 v75, v75, v91
	v_add_f32_e32 v76, v76, v92
	v_add_f32_e32 v77, v77, v93
	ds_bpermute_b32 v78, v50, v62
	ds_bpermute_b32 v79, v50, v63
	ds_bpermute_b32 v80, v50, v64
	ds_bpermute_b32 v81, v50, v65
	ds_bpermute_b32 v82, v50, v66
	ds_bpermute_b32 v83, v50, v67
	ds_bpermute_b32 v84, v50, v68
	ds_bpermute_b32 v85, v50, v69
	s_waitcnt lgkmcnt(0)
	v_add_f32_e32 v62, v62, v78
	v_add_f32_e32 v63, v63, v79
	v_add_f32_e32 v64, v64, v80
	v_add_f32_e32 v65, v65, v81
	v_add_f32_e32 v66, v66, v82
	v_add_f32_e32 v67, v67, v83
	v_add_f32_e32 v68, v68, v84
	v_add_f32_e32 v69, v69, v85
	ds_bpermute_b32 v86, v50, v70
	ds_bpermute_b32 v87, v50, v71
	ds_bpermute_b32 v88, v50, v72
	ds_bpermute_b32 v89, v50, v73
	ds_bpermute_b32 v90, v50, v74
	ds_bpermute_b32 v91, v50, v75
	ds_bpermute_b32 v92, v50, v76
	ds_bpermute_b32 v93, v50, v77
	s_waitcnt lgkmcnt(0)
	v_add_f32_e32 v70, v70, v86
	v_add_f32_e32 v71, v71, v87
	v_add_f32_e32 v72, v72, v88
	v_add_f32_e32 v73, v73, v89
	v_add_f32_e32 v74, v74, v90
	v_add_f32_e32 v75, v75, v91
	v_add_f32_e32 v76, v76, v92
	v_add_f32_e32 v77, v77, v93
	ds_bpermute_b32 v78, v51, v62
	ds_bpermute_b32 v79, v51, v63
	ds_bpermute_b32 v80, v51, v64
	ds_bpermute_b32 v81, v51, v65
	ds_bpermute_b32 v82, v51, v66
	ds_bpermute_b32 v83, v51, v67
	ds_bpermute_b32 v84, v51, v68
	ds_bpermute_b32 v85, v51, v69
	s_waitcnt lgkmcnt(0)
	v_add_f32_e32 v62, v62, v78
	v_add_f32_e32 v63, v63, v79
	v_add_f32_e32 v64, v64, v80
	v_add_f32_e32 v65, v65, v81
	v_add_f32_e32 v66, v66, v82
	v_add_f32_e32 v67, v67, v83
	v_add_f32_e32 v68, v68, v84
	v_add_f32_e32 v69, v69, v85
	ds_bpermute_b32 v86, v51, v70
	ds_bpermute_b32 v87, v51, v71
	ds_bpermute_b32 v88, v51, v72
	ds_bpermute_b32 v89, v51, v73
	ds_bpermute_b32 v90, v51, v74
	ds_bpermute_b32 v91, v51, v75
	ds_bpermute_b32 v92, v51, v76
	ds_bpermute_b32 v93, v51, v77
	s_waitcnt lgkmcnt(0)
	v_add_f32_e32 v70, v70, v86
	v_add_f32_e32 v71, v71, v87
	v_add_f32_e32 v72, v72, v88
	v_add_f32_e32 v73, v73, v89
	v_add_f32_e32 v74, v74, v90
	v_add_f32_e32 v75, v75, v91
	v_add_f32_e32 v76, v76, v92
	v_add_f32_e32 v77, v77, v93
	ds_bpermute_b32 v78, v52, v62
	ds_bpermute_b32 v79, v52, v63
	ds_bpermute_b32 v80, v52, v64
	ds_bpermute_b32 v81, v52, v65
	ds_bpermute_b32 v82, v52, v66
	ds_bpermute_b32 v83, v52, v67
	ds_bpermute_b32 v84, v52, v68
	ds_bpermute_b32 v85, v52, v69
	s_waitcnt lgkmcnt(0)
	v_add_f32_e32 v62, v62, v78
	v_add_f32_e32 v63, v63, v79
	v_add_f32_e32 v64, v64, v80
	v_add_f32_e32 v65, v65, v81
	v_add_f32_e32 v66, v66, v82
	v_add_f32_e32 v67, v67, v83
	v_add_f32_e32 v68, v68, v84
	v_add_f32_e32 v69, v69, v85
	ds_bpermute_b32 v86, v52, v70
	ds_bpermute_b32 v87, v52, v71
	ds_bpermute_b32 v88, v52, v72
	ds_bpermute_b32 v89, v52, v73
	ds_bpermute_b32 v90, v52, v74
	ds_bpermute_b32 v91, v52, v75
	ds_bpermute_b32 v92, v52, v76
	ds_bpermute_b32 v93, v52, v77
	s_waitcnt lgkmcnt(0)
	v_add_f32_e32 v70, v70, v86
	v_add_f32_e32 v71, v71, v87
	v_add_f32_e32 v72, v72, v88
	v_add_f32_e32 v73, v73, v89
	v_add_f32_e32 v74, v74, v90
	v_add_f32_e32 v75, v75, v91
	v_add_f32_e32 v76, v76, v92
	v_add_f32_e32 v77, v77, v93
	v_fmamk_f32 v62, v62, 0x3c000000, v247
	v_fmamk_f32 v63, v63, 0x3c000000, v247
	v_fmamk_f32 v64, v64, 0x3c000000, v247
	v_fmamk_f32 v65, v65, 0x3c000000, v247
	v_fmamk_f32 v66, v66, 0x3c000000, v247
	v_fmamk_f32 v67, v67, 0x3c000000, v247
	v_fmamk_f32 v68, v68, 0x3c000000, v247
	v_fmamk_f32 v69, v69, 0x3c000000, v247
	v_fmamk_f32 v70, v70, 0x3c000000, v247
	v_fmamk_f32 v71, v71, 0x3c000000, v247
	v_fmamk_f32 v72, v72, 0x3c000000, v247
	v_fmamk_f32 v73, v73, 0x3c000000, v247
	v_fmamk_f32 v74, v74, 0x3c000000, v247
	v_fmamk_f32 v75, v75, 0x3c000000, v247
	v_fmamk_f32 v76, v76, 0x3c000000, v247
	v_fmamk_f32 v77, v77, 0x3c000000, v247
	v_rsq_f32_e32 v62, v62
	v_rsq_f32_e32 v63, v63
	v_rsq_f32_e32 v64, v64
	v_rsq_f32_e32 v65, v65
	v_rsq_f32_e32 v66, v66
	v_rsq_f32_e32 v67, v67
	v_rsq_f32_e32 v68, v68
	v_rsq_f32_e32 v69, v69
	v_rsq_f32_e32 v70, v70
	v_rsq_f32_e32 v71, v71
	v_rsq_f32_e32 v72, v72
	v_rsq_f32_e32 v73, v73
	v_rsq_f32_e32 v74, v74
	v_rsq_f32_e32 v75, v75
	v_rsq_f32_e32 v76, v76
	v_rsq_f32_e32 v77, v77
	v_mul_f32_e32 v78, v53, v62
	v_mul_f32_e32 v79, v53, v63
	v_mul_f32_e32 v80, v53, v64
	v_mul_f32_e32 v81, v53, v65
	v_mul_f32_e32 v82, v53, v66
	v_mul_f32_e32 v83, v53, v67
	v_mul_f32_e32 v84, v53, v68
	v_mul_f32_e32 v85, v53, v69
	v_mul_f32_e32 v86, v53, v70
	v_mul_f32_e32 v87, v53, v71
	v_mul_f32_e32 v88, v53, v72
	v_mul_f32_e32 v89, v53, v73
	v_mul_f32_e32 v90, v53, v74
	v_mul_f32_e32 v91, v53, v75
	v_mul_f32_e32 v92, v53, v76
	v_mul_f32_e32 v93, v53, v77
	v_pk_mul_f32 v[100:101], v[0:1], v[100:101]
	v_pk_mul_f32 v[102:103], v[2:3], v[102:103]
	v_pk_mul_f32 v[104:105], v[4:5], v[104:105]
	v_pk_mul_f32 v[106:107], v[6:7], v[106:107]
	v_pk_mul_f32 v[100:101], v[100:101], v[78:79] op_sel_hi:[1,0]
	v_pk_mul_f32 v[102:103], v[102:103], v[78:79] op_sel_hi:[1,0]
	v_pk_mul_f32 v[104:105], v[104:105], v[78:79] op_sel_hi:[1,0]
	v_pk_mul_f32 v[106:107], v[106:107], v[78:79] op_sel_hi:[1,0]
	v_cvt_pk_bf16_f32 v100, v100, v101
	v_cvt_pk_bf16_f32 v101, v102, v103
	v_cvt_pk_bf16_f32 v102, v104, v105
	v_cvt_pk_bf16_f32 v103, v106, v107
	global_store_dwordx4 v13, v[100:103], s[14:15]
	s_add_u32 s14, s14, 0x400000
	s_addc_u32 s15, s15, 0
	v_mov_b32_e32 v54, v79
	v_pk_mul_f32 v[108:109], v[0:1], v[108:109]
	v_pk_mul_f32 v[110:111], v[2:3], v[110:111]
	v_pk_mul_f32 v[112:113], v[4:5], v[112:113]
	v_pk_mul_f32 v[114:115], v[6:7], v[114:115]
	v_pk_mul_f32 v[108:109], v[108:109], v[54:55] op_sel_hi:[1,0]
	v_pk_mul_f32 v[110:111], v[110:111], v[54:55] op_sel_hi:[1,0]
	v_pk_mul_f32 v[112:113], v[112:113], v[54:55] op_sel_hi:[1,0]
	v_pk_mul_f32 v[114:115], v[114:115], v[54:55] op_sel_hi:[1,0]
	v_cvt_pk_bf16_f32 v108, v108, v109
	v_cvt_pk_bf16_f32 v109, v110, v111
	v_cvt_pk_bf16_f32 v110, v112, v113
	v_cvt_pk_bf16_f32 v111, v114, v115
	global_store_dwordx4 v13, v[108:111], s[14:15]
	s_add_u32 s14, s14, 0x400000
	s_addc_u32 s15, s15, 0
	v_pk_mul_f32 v[116:117], v[0:1], v[116:117]
	v_pk_mul_f32 v[118:119], v[2:3], v[118:119]
	v_pk_mul_f32 v[120:121], v[4:5], v[120:121]
	v_pk_mul_f32 v[122:123], v[6:7], v[122:123]
	v_pk_mul_f32 v[116:117], v[116:117], v[80:81] op_sel_hi:[1,0]
	v_pk_mul_f32 v[118:119], v[118:119], v[80:81] op_sel_hi:[1,0]
	v_pk_mul_f32 v[120:121], v[120:121], v[80:81] op_sel_hi:[1,0]
	v_pk_mul_f32 v[122:123], v[122:123], v[80:81] op_sel_hi:[1,0]
	v_cvt_pk_bf16_f32 v116, v116, v117
	v_cvt_pk_bf16_f32 v117, v118, v119
	v_cvt_pk_bf16_f32 v118, v120, v121
	v_cvt_pk_bf16_f32 v119, v122, v123
	global_store_dwordx4 v13, v[116:119], s[14:15]
	s_add_u32 s14, s14, 0x400000
	s_addc_u32 s15, s15, 0
	v_mov_b32_e32 v54, v81
	v_pk_mul_f32 v[124:125], v[0:1], v[124:125]
	v_pk_mul_f32 v[126:127], v[2:3], v[126:127]
	v_pk_mul_f32 v[128:129], v[4:5], v[128:129]
	v_pk_mul_f32 v[130:131], v[6:7], v[130:131]
	v_pk_mul_f32 v[124:125], v[124:125], v[54:55] op_sel_hi:[1,0]
	v_pk_mul_f32 v[126:127], v[126:127], v[54:55] op_sel_hi:[1,0]
	v_pk_mul_f32 v[128:129], v[128:129], v[54:55] op_sel_hi:[1,0]
	v_pk_mul_f32 v[130:131], v[130:131], v[54:55] op_sel_hi:[1,0]
	v_cvt_pk_bf16_f32 v124, v124, v125
	v_cvt_pk_bf16_f32 v125, v126, v127
	v_cvt_pk_bf16_f32 v126, v128, v129
	v_cvt_pk_bf16_f32 v127, v130, v131
	global_store_dwordx4 v13, v[124:127], s[14:15]
	s_add_u32 s14, s14, 0x400000
	s_addc_u32 s15, s15, 0
	v_pk_mul_f32 v[132:133], v[0:1], v[132:133]
	v_pk_mul_f32 v[134:135], v[2:3], v[134:135]
	v_pk_mul_f32 v[136:137], v[4:5], v[136:137]
	v_pk_mul_f32 v[138:139], v[6:7], v[138:139]
	v_pk_mul_f32 v[132:133], v[132:133], v[82:83] op_sel_hi:[1,0]
	v_pk_mul_f32 v[134:135], v[134:135], v[82:83] op_sel_hi:[1,0]
	v_pk_mul_f32 v[136:137], v[136:137], v[82:83] op_sel_hi:[1,0]
	v_pk_mul_f32 v[138:139], v[138:139], v[82:83] op_sel_hi:[1,0]
	v_cvt_pk_bf16_f32 v132, v132, v133
	v_cvt_pk_bf16_f32 v133, v134, v135
	v_cvt_pk_bf16_f32 v134, v136, v137
	v_cvt_pk_bf16_f32 v135, v138, v139
	global_store_dwordx4 v13, v[132:135], s[14:15]
	s_add_u32 s14, s14, 0x400000
	s_addc_u32 s15, s15, 0
	v_mov_b32_e32 v54, v83
	v_pk_mul_f32 v[140:141], v[0:1], v[140:141]
	v_pk_mul_f32 v[142:143], v[2:3], v[142:143]
	v_pk_mul_f32 v[144:145], v[4:5], v[144:145]
	v_pk_mul_f32 v[146:147], v[6:7], v[146:147]
	v_pk_mul_f32 v[140:141], v[140:141], v[54:55] op_sel_hi:[1,0]
	v_pk_mul_f32 v[142:143], v[142:143], v[54:55] op_sel_hi:[1,0]
	v_pk_mul_f32 v[144:145], v[144:145], v[54:55] op_sel_hi:[1,0]
	v_pk_mul_f32 v[146:147], v[146:147], v[54:55] op_sel_hi:[1,0]
	v_cvt_pk_bf16_f32 v140, v140, v141
	v_cvt_pk_bf16_f32 v141, v142, v143
	v_cvt_pk_bf16_f32 v142, v144, v145
	v_cvt_pk_bf16_f32 v143, v146, v147
	global_store_dwordx4 v13, v[140:143], s[14:15]
	s_add_u32 s14, s14, 0x400000
	s_addc_u32 s15, s15, 0
	v_pk_mul_f32 v[148:149], v[0:1], v[148:149]
	v_pk_mul_f32 v[150:151], v[2:3], v[150:151]
	v_pk_mul_f32 v[152:153], v[4:5], v[152:153]
	v_pk_mul_f32 v[154:155], v[6:7], v[154:155]
	v_pk_mul_f32 v[148:149], v[148:149], v[84:85] op_sel_hi:[1,0]
	v_pk_mul_f32 v[150:151], v[150:151], v[84:85] op_sel_hi:[1,0]
	v_pk_mul_f32 v[152:153], v[152:153], v[84:85] op_sel_hi:[1,0]
	v_pk_mul_f32 v[154:155], v[154:155], v[84:85] op_sel_hi:[1,0]
	v_cvt_pk_bf16_f32 v148, v148, v149
	v_cvt_pk_bf16_f32 v149, v150, v151
	v_cvt_pk_bf16_f32 v150, v152, v153
	v_cvt_pk_bf16_f32 v151, v154, v155
	global_store_dwordx4 v13, v[148:151], s[14:15]
	s_add_u32 s14, s14, 0x400000
	s_addc_u32 s15, s15, 0
	v_mov_b32_e32 v54, v85
	v_pk_mul_f32 v[156:157], v[0:1], v[156:157]
	v_pk_mul_f32 v[158:159], v[2:3], v[158:159]
	v_pk_mul_f32 v[160:161], v[4:5], v[160:161]
	v_pk_mul_f32 v[162:163], v[6:7], v[162:163]
	v_pk_mul_f32 v[156:157], v[156:157], v[54:55] op_sel_hi:[1,0]
	v_pk_mul_f32 v[158:159], v[158:159], v[54:55] op_sel_hi:[1,0]
	v_pk_mul_f32 v[160:161], v[160:161], v[54:55] op_sel_hi:[1,0]
	v_pk_mul_f32 v[162:163], v[162:163], v[54:55] op_sel_hi:[1,0]
	v_cvt_pk_bf16_f32 v156, v156, v157
	v_cvt_pk_bf16_f32 v157, v158, v159
	v_cvt_pk_bf16_f32 v158, v160, v161
	v_cvt_pk_bf16_f32 v159, v162, v163
	global_store_dwordx4 v13, v[156:159], s[14:15]
	s_add_u32 s14, s14, 0x400000
	s_addc_u32 s15, s15, 0
	v_pk_mul_f32 v[164:165], v[0:1], v[164:165]
	v_pk_mul_f32 v[166:167], v[2:3], v[166:167]
	v_pk_mul_f32 v[168:169], v[4:5], v[168:169]
	v_pk_mul_f32 v[170:171], v[6:7], v[170:171]
	v_pk_mul_f32 v[164:165], v[164:165], v[86:87] op_sel_hi:[1,0]
	v_pk_mul_f32 v[166:167], v[166:167], v[86:87] op_sel_hi:[1,0]
	v_pk_mul_f32 v[168:169], v[168:169], v[86:87] op_sel_hi:[1,0]
	v_pk_mul_f32 v[170:171], v[170:171], v[86:87] op_sel_hi:[1,0]
	v_cvt_pk_bf16_f32 v164, v164, v165
	v_cvt_pk_bf16_f32 v165, v166, v167
	v_cvt_pk_bf16_f32 v166, v168, v169
	v_cvt_pk_bf16_f32 v167, v170, v171
	global_store_dwordx4 v13, v[164:167], s[14:15]
	s_add_u32 s14, s14, 0x400000
	s_addc_u32 s15, s15, 0
	v_mov_b32_e32 v54, v87
	v_pk_mul_f32 v[172:173], v[0:1], v[172:173]
	v_pk_mul_f32 v[174:175], v[2:3], v[174:175]
	v_pk_mul_f32 v[176:177], v[4:5], v[176:177]
	v_pk_mul_f32 v[178:179], v[6:7], v[178:179]
	v_pk_mul_f32 v[172:173], v[172:173], v[54:55] op_sel_hi:[1,0]
	v_pk_mul_f32 v[174:175], v[174:175], v[54:55] op_sel_hi:[1,0]
	v_pk_mul_f32 v[176:177], v[176:177], v[54:55] op_sel_hi:[1,0]
	v_pk_mul_f32 v[178:179], v[178:179], v[54:55] op_sel_hi:[1,0]
	v_cvt_pk_bf16_f32 v172, v172, v173
	v_cvt_pk_bf16_f32 v173, v174, v175
	v_cvt_pk_bf16_f32 v174, v176, v177
	v_cvt_pk_bf16_f32 v175, v178, v179
	global_store_dwordx4 v13, v[172:175], s[14:15]
	s_add_u32 s14, s14, 0x400000
	s_addc_u32 s15, s15, 0
	v_pk_mul_f32 v[180:181], v[0:1], v[180:181]
	v_pk_mul_f32 v[182:183], v[2:3], v[182:183]
	v_pk_mul_f32 v[184:185], v[4:5], v[184:185]
	v_pk_mul_f32 v[186:187], v[6:7], v[186:187]
	v_pk_mul_f32 v[180:181], v[180:181], v[88:89] op_sel_hi:[1,0]
	v_pk_mul_f32 v[182:183], v[182:183], v[88:89] op_sel_hi:[1,0]
	v_pk_mul_f32 v[184:185], v[184:185], v[88:89] op_sel_hi:[1,0]
	v_pk_mul_f32 v[186:187], v[186:187], v[88:89] op_sel_hi:[1,0]
	v_cvt_pk_bf16_f32 v180, v180, v181
	v_cvt_pk_bf16_f32 v181, v182, v183
	v_cvt_pk_bf16_f32 v182, v184, v185
	v_cvt_pk_bf16_f32 v183, v186, v187
	global_store_dwordx4 v13, v[180:183], s[14:15]
	s_add_u32 s14, s14, 0x400000
	s_addc_u32 s15, s15, 0
	v_mov_b32_e32 v54, v89
	v_pk_mul_f32 v[188:189], v[0:1], v[188:189]
	v_pk_mul_f32 v[190:191], v[2:3], v[190:191]
	v_pk_mul_f32 v[192:193], v[4:5], v[192:193]
	v_pk_mul_f32 v[194:195], v[6:7], v[194:195]
	v_pk_mul_f32 v[188:189], v[188:189], v[54:55] op_sel_hi:[1,0]
	v_pk_mul_f32 v[190:191], v[190:191], v[54:55] op_sel_hi:[1,0]
	v_pk_mul_f32 v[192:193], v[192:193], v[54:55] op_sel_hi:[1,0]
	v_pk_mul_f32 v[194:195], v[194:195], v[54:55] op_sel_hi:[1,0]
	v_cvt_pk_bf16_f32 v188, v188, v189
	v_cvt_pk_bf16_f32 v189, v190, v191
	v_cvt_pk_bf16_f32 v190, v192, v193
	v_cvt_pk_bf16_f32 v191, v194, v195
	global_store_dwordx4 v13, v[188:191], s[14:15]
	s_add_u32 s14, s14, 0x400000
	s_addc_u32 s15, s15, 0
	v_pk_mul_f32 v[196:197], v[0:1], v[196:197]
	v_pk_mul_f32 v[198:199], v[2:3], v[198:199]
	v_pk_mul_f32 v[200:201], v[4:5], v[200:201]
	v_pk_mul_f32 v[202:203], v[6:7], v[202:203]
	v_pk_mul_f32 v[196:197], v[196:197], v[90:91] op_sel_hi:[1,0]
	v_pk_mul_f32 v[198:199], v[198:199], v[90:91] op_sel_hi:[1,0]
	v_pk_mul_f32 v[200:201], v[200:201], v[90:91] op_sel_hi:[1,0]
	v_pk_mul_f32 v[202:203], v[202:203], v[90:91] op_sel_hi:[1,0]
	v_cvt_pk_bf16_f32 v196, v196, v197
	v_cvt_pk_bf16_f32 v197, v198, v199
	v_cvt_pk_bf16_f32 v198, v200, v201
	v_cvt_pk_bf16_f32 v199, v202, v203
	global_store_dwordx4 v13, v[196:199], s[14:15]
	s_add_u32 s14, s14, 0x400000
	s_addc_u32 s15, s15, 0
	v_mov_b32_e32 v54, v91
	v_pk_mul_f32 v[204:205], v[0:1], v[204:205]
	v_pk_mul_f32 v[206:207], v[2:3], v[206:207]
	v_pk_mul_f32 v[208:209], v[4:5], v[208:209]
	v_pk_mul_f32 v[210:211], v[6:7], v[210:211]
	v_pk_mul_f32 v[204:205], v[204:205], v[54:55] op_sel_hi:[1,0]
	v_pk_mul_f32 v[206:207], v[206:207], v[54:55] op_sel_hi:[1,0]
	v_pk_mul_f32 v[208:209], v[208:209], v[54:55] op_sel_hi:[1,0]
	v_pk_mul_f32 v[210:211], v[210:211], v[54:55] op_sel_hi:[1,0]
	v_cvt_pk_bf16_f32 v204, v204, v205
	v_cvt_pk_bf16_f32 v205, v206, v207
	v_cvt_pk_bf16_f32 v206, v208, v209
	v_cvt_pk_bf16_f32 v207, v210, v211
	global_store_dwordx4 v13, v[204:207], s[14:15]
	s_add_u32 s14, s14, 0x400000
	s_addc_u32 s15, s15, 0
	v_pk_mul_f32 v[212:213], v[0:1], v[212:213]
	v_pk_mul_f32 v[214:215], v[2:3], v[214:215]
	v_pk_mul_f32 v[216:217], v[4:5], v[216:217]
	v_pk_mul_f32 v[218:219], v[6:7], v[218:219]
	v_pk_mul_f32 v[212:213], v[212:213], v[92:93] op_sel_hi:[1,0]
	v_pk_mul_f32 v[214:215], v[214:215], v[92:93] op_sel_hi:[1,0]
	v_pk_mul_f32 v[216:217], v[216:217], v[92:93] op_sel_hi:[1,0]
	v_pk_mul_f32 v[218:219], v[218:219], v[92:93] op_sel_hi:[1,0]
	v_cvt_pk_bf16_f32 v212, v212, v213
	v_cvt_pk_bf16_f32 v213, v214, v215
	v_cvt_pk_bf16_f32 v214, v216, v217
	v_cvt_pk_bf16_f32 v215, v218, v219
	global_store_dwordx4 v13, v[212:215], s[14:15]
	s_add_u32 s14, s14, 0x400000
	s_addc_u32 s15, s15, 0
	v_mov_b32_e32 v54, v93
	v_pk_mul_f32 v[220:221], v[0:1], v[220:221]
	v_pk_mul_f32 v[222:223], v[2:3], v[222:223]
	v_pk_mul_f32 v[224:225], v[4:5], v[224:225]
	v_pk_mul_f32 v[226:227], v[6:7], v[226:227]
	v_pk_mul_f32 v[220:221], v[220:221], v[54:55] op_sel_hi:[1,0]
	v_pk_mul_f32 v[222:223], v[222:223], v[54:55] op_sel_hi:[1,0]
	v_pk_mul_f32 v[224:225], v[224:225], v[54:55] op_sel_hi:[1,0]
	v_pk_mul_f32 v[226:227], v[226:227], v[54:55] op_sel_hi:[1,0]
	v_cvt_pk_bf16_f32 v220, v220, v221
	v_cvt_pk_bf16_f32 v221, v222, v223
	v_cvt_pk_bf16_f32 v222, v224, v225
	v_cvt_pk_bf16_f32 v223, v226, v227
	global_store_dwordx4 v13, v[220:223], s[14:15]
